# priority raise for the single DeltaNet state wave of each workgroup (timing only)
# speedup vs baseline: 1.0482x; 1.0022x over previous
; __device__ __forceinline__ int opaque_tid() { int t = threadIdx.x; asm volatile("" : "+v"(t)); return t; }
; #define LAS __attribute__((address_space(3)))
; #define BAR_LDS() do { asm volatile("s_waitcnt lgkmcnt(0)" ::: "memory"); __builtin_amdgcn_s_barrier(); asm volatile("" ::: "memory"); } while (0)
; #define MFMA32(a, b, c) __builtin_amdgcn_mfma_f32_32x32x16_bf16((a), (b), (c), 0, 0, 0)
; template <int VAR> __device__ __forceinline__ void dn_scan3(LAS unsigned char* lds, const bf16_t* P, const float* AB, const bf16_t* TP, bf16_t* OB) {
;     ...
;             f32x16 S[4];
; #pragma unroll
;             for (int kt = 0; kt < 4; ++kt)
; #pragma unroll
;                 for (int x = 0; x < 16; ++x) S[kt][x] = 0.f;
;             BAR_LDS();
;             for (int step = 0; step < 260; ++step) {
;                 const int lane = opaque_tid() & 63, r = lane & 31, h = lane >> 5;
;                 LAS unsigned char* base = lds + (step & 1) * DN_DIR;
;                 LAS bf16_t* Kb = (LAS bf16_t*)(base + DN_KB); LAS bf16_t* Qb = (LAS bf16_t*)(base + DN_QB); LAS bf16_t* Vb = (LAS bf16_t*)(base + DN_VB);
;                 LAS bf16_t* Tb = (LAS bf16_t*)(base + DN_TB); LAS bf16_t* Ab = (LAS bf16_t*)(base + DN_AB);
;                 LAS float* sc_beta = (LAS float*)(base + DN_SC); LAS float* sc_eg = sc_beta + 128; LAS float* sc_tail = sc_beta + 192; LAS float* sc_dl = sc_beta + 256;
;                 int rb; bool f_; dn_step_rb(step, dir, b, rb, f_);
;                 if (VAR != 2) {
;                 f32x16 KS[2], QS[2];
; #pragma unroll
;                 for (int mt = 0; mt < 2; ++mt)
; #pragma unroll
;                     for (int x = 0; x < 16; ++x) { KS[mt][x] = 0.f; QS[mt][x] = 0.f; }
; #pragma unroll
;                 for (int ks = 0; ks < 8; ++ks) {
;                     const bf16x8 sp = pack_step(S[ks >> 1], ks & 1);
; #pragma unroll
;                     for (int mt = 0; mt < 2; ++mt) { KS[mt] = MFMA32(frag_perm(Kb, 136, 32 * mt + r, ks, h), sp, KS[mt]); QS[mt] = MFMA32(frag_perm(Qb, 136, 32 * mt + r, ks, h), sp, QS[mt]); }
.Ldn_full:
	s_setprio 3
	v_mov_b32_e32 v2, 0
	s_mov_b32 s40, 0
	v_mov_b32_e32 v3, v2
	v_mov_b32_e32 v4, v2
	v_mov_b32_e32 v5, v2
	v_mov_b32_e32 v6, v2
	v_mov_b32_e32 v7, v2
	v_mov_b32_e32 v8, v2
	v_mov_b32_e32 v9, v2
	v_mov_b32_e32 v10, v2
	v_mov_b32_e32 v11, v2
	v_mov_b32_e32 v12, v2
	v_mov_b32_e32 v13, v2
	v_mov_b32_e32 v14, v2
	v_mov_b32_e32 v15, v2
	v_mov_b32_e32 v16, v2
	v_mov_b32_e32 v17, v2
	v_mov_b32_e32 v18, v2
	v_mov_b32_e32 v19, v2
	v_mov_b32_e32 v20, v2
	v_mov_b32_e32 v21, v2
	v_mov_b32_e32 v22, v2
	v_mov_b32_e32 v23, v2
	v_mov_b32_e32 v24, v2
	v_mov_b32_e32 v25, v2
	v_mov_b32_e32 v26, v2
	v_mov_b32_e32 v27, v2
	v_mov_b32_e32 v28, v2
	v_mov_b32_e32 v29, v2
	v_mov_b32_e32 v30, v2
	v_mov_b32_e32 v31, v2
	v_mov_b32_e32 v32, v2
	v_mov_b32_e32 v33, v2
	v_mov_b32_e32 v34, v2
	v_mov_b32_e32 v35, v2
	v_mov_b32_e32 v36, v2
	v_mov_b32_e32 v37, v2
	v_mov_b32_e32 v38, v2
	v_mov_b32_e32 v39, v2
	v_mov_b32_e32 v40, v2
	v_mov_b32_e32 v41, v2
	v_mov_b32_e32 v42, v2
	v_mov_b32_e32 v43, v2
	v_mov_b32_e32 v44, v2
	v_mov_b32_e32 v45, v2
	v_mov_b32_e32 v46, v2
	v_mov_b32_e32 v47, v2
	v_mov_b32_e32 v48, v2
	v_mov_b32_e32 v49, v2
	v_mov_b32_e32 v50, v2
	v_mov_b32_e32 v51, v2
	v_mov_b32_e32 v52, v2
	v_mov_b32_e32 v53, v2
	v_mov_b32_e32 v54, v2
	v_mov_b32_e32 v55, v2
	v_mov_b32_e32 v56, v2
	v_mov_b32_e32 v57, v2
	v_mov_b32_e32 v58, v2
	v_mov_b32_e32 v59, v2
	v_mov_b32_e32 v60, v2
	v_mov_b32_e32 v61, v2
	v_mov_b32_e32 v62, v2
	v_mov_b32_e32 v63, v2
	v_mov_b32_e32 v64, v2
	v_mov_b32_e32 v65, v2
	v_and_b32_e32 v212, 31, v188
	v_bfe_u32 v213, v188, 5, 1
	v_mul_u32_u24_e32 v214, 0x110, v212
	v_lshl_add_u32 v207, v213, 4, v214
	v_mul_u32_u24_e32 v214, 0x90, v212
	v_lshl_add_u32 v210, v213, 4, v214
	v_lshlrev_b32_e32 v214, 1, v212
	v_lshl_add_u32 v214, v213, 10, v214
	v_add_u32_e32 v208, s18, v214
	v_lshlrev_b32_e32 v214, 4, v213
	v_add_u32_e32 v209, 0x11000, v214
	v_bfe_u32 v214, v188, 2, 2
	v_and_b32_e32 v215, 3, v188
	v_lshlrev_b32_e32 v215, 3, v215
	v_bfe_u32 v216, v188, 4, 1
	v_lshl_add_u32 v215, v216, 5, v215
	v_lshlrev_b32_e32 v216, 3, v214
	v_lshl_add_u32 v216, v213, 2, v216
	v_and_b32_e32 v217, 3, v214
	v_add_u32_e32 v217, v217, v216
	v_mul_u32_u24_e32 v217, 0x110, v217
	v_add_u32_e32 v211, v217, v215
	v_add_u32_e32 v217, 1, v214
	v_and_b32_e32 v217, 3, v217
	v_add_u32_e32 v217, v217, v216
	v_mul_u32_u24_e32 v217, 0x110, v217
	v_add_u32_e32 v201, v217, v215
	v_add_u32_e32 v217, 2, v214
	v_and_b32_e32 v217, 3, v217
	v_add_u32_e32 v217, v217, v216
	v_mul_u32_u24_e32 v217, 0x110, v217
	v_add_u32_e32 v180, v217, v215
	v_add_u32_e32 v217, 3, v214
	v_and_b32_e32 v217, 3, v217
	v_add_u32_e32 v217, v217, v216
	v_mul_u32_u24_e32 v217, 0x110, v217
	v_add_u32_e32 v217, v217, v215
	v_lshl_or_b32 v180, v217, 16, v180
	s_and_b32 s57, s54, 1
	s_lshr_b32 s45, s54, 5
	s_lshl_b32 s55, s45, 2
	s_addk_i32 s55, 0x200
	s_lshl_b32 s56, s45, 8
	s_bfe_u32 s48, s54, 0x40001
	s_lshl_b32 s48, s48, 8
	s_add_i32 s48, s48, s18
	s_add_u32 s58, s8, s48
	s_addc_u32 s59, s9, 0
	s_mul_i32 s49, s57, 63
	s_mov_b32 s60, 0
	s_lshl_b32 s61, s57, 15
	s_sub_i32 s61, 0x4000, s61
	s_lshl_b32 s62, s61, 1
	v_and_b32_e32 v212, 63, v188
	v_lshrrev_b32_e32 v213, 4, v212
	v_and_b32_e32 v214, 15, v212
	v_lshlrev_b32_e32 v214, 2, v214
	v_lshl_add_u32 v0, v213, 8, v214
	v_add_u32_e32 v0, s18, v0
	v_xor_b32_e32 v215, s49, v213
	v_lshl_add_u32 v194, v215, 12, v214
.LBB0_377:
	s_bitcmp1_b32 s40, 0
	s_cselect_b32 s41, 0x11600, 0
	v_add_u32_e32 v212, s41, v207
	v_add_u32_e32 v214, s41, v209
	v_add_u32_e32 v213, s41, v208
	v_add_u32_e32 v215, s41, v210
	s_add_i32 s42, s41, 0x11400
	v_mov_b32_e32 v217, s42
	v_add_u32_e32 v179, s41, v0
	s_add_i32 s44, s40, -4
	s_cmp_lt_u32 s40, 4
	s_cselect_b32 s44, s40, s44
	s_cselect_b32 s45, 3, 0xff
	s_cselect_b32 s48, s55, s56
	s_sub_i32 s45, s45, s44
	s_cmp_eq_u32 s57, 0
	s_cselect_b32 s44, s44, s45
	s_add_i32 s44, s44, s48
	s_lshl_b32 s44, s44, 18
	s_add_u32 s42, s58, s44
	s_addc_u32 s43, s59, 0
	ds_read_b128 v[138:141], v212 offset:0
	ds_read_b128 v[142:145], v212 offset:32
	ds_read_b128 v[146:149], v212 offset:64
	ds_read_b128 v[150:153], v212 offset:96
	ds_read_b128 v[154:157], v212 offset:128
	ds_read_b128 v[158:161], v212 offset:160
	v_cvt_pk_bf16_f32 v218, v50, v51
	v_cvt_pk_bf16_f32 v220, v54, v55
	v_cvt_pk_bf16_f32 v219, v52, v53
	v_cvt_pk_bf16_f32 v221, v56, v57
	v_cvt_pk_bf16_f32 v222, v58, v59
	v_cvt_pk_bf16_f32 v224, v62, v63
	v_cvt_pk_bf16_f32 v223, v60, v61
	v_cvt_pk_bf16_f32 v225, v64, v65
	v_permlane32_swap_b32_e32 v218, v220
	v_permlane32_swap_b32_e32 v219, v221
	v_permlane32_swap_b32_e32 v222, v224
	v_permlane32_swap_b32_e32 v223, v225
	ds_read_b128 v[162:165], v212 offset:192
	ds_read_b128 v[166:169], v212 offset:224
	s_waitcnt lgkmcnt(7)
	v_mfma_f32_32x32x16_bf16 v[66:81], v[138:141], v[218:221], 0
	v_cvt_pk_bf16_f32 v226, v34, v35
	v_cvt_pk_bf16_f32 v228, v38, v39
	v_cvt_pk_bf16_f32 v227, v36, v37
	v_cvt_pk_bf16_f32 v229, v40, v41
	v_permlane32_swap_b32_e32 v226, v228
	ds_read_b128 v[138:141], v212 offset:8704
	v_permlane32_swap_b32_e32 v227, v229
	ds_read_b128 v[170:173], v212 offset:8736
	s_waitcnt lgkmcnt(8)
	v_mfma_f32_32x32x16_bf16 v[66:81], v[142:145], v[222:225], v[66:81]
	v_cvt_pk_bf16_f32 v230, v42, v43
	v_cvt_pk_bf16_f32 v232, v46, v47
	v_cvt_pk_bf16_f32 v231, v44, v45
	v_cvt_pk_bf16_f32 v233, v48, v49
	v_permlane32_swap_b32_e32 v230, v232
	ds_read_b128 v[142:145], v212 offset:8768
	v_permlane32_swap_b32_e32 v231, v233
	s_waitcnt lgkmcnt(8)
	v_mfma_f32_32x32x16_bf16 v[66:81], v[146:149], v[226:229], v[66:81]
	v_cvt_pk_bf16_f32 v234, v18, v19
	v_cvt_pk_bf16_f32 v236, v22, v23
	v_cvt_pk_bf16_f32 v235, v20, v21
	v_cvt_pk_bf16_f32 v237, v24, v25
	v_permlane32_swap_b32_e32 v234, v236
	ds_read_b128 v[146:149], v212 offset:8800
	v_permlane32_swap_b32_e32 v235, v237
	s_waitcnt lgkmcnt(8)
; #define LAS __attribute__((address_space(3)))
; #define MFMA32(a, b, c) __builtin_amdgcn_mfma_f32_32x32x16_bf16((a), (b), (c), 0, 0, 0)
; template <int VAR> __device__ __forceinline__ void dn_scan3(LAS unsigned char* lds, const bf16_t* P, const float* AB, const bf16_t* TP, bf16_t* OB) {
;     ...
;                 for (int ks = 0; ks < 8; ++ks) {
;                     const bf16x8 sp = pack_step(S[ks >> 1], ks & 1);
; #pragma unroll
;                     for (int mt = 0; mt < 2; ++mt) { KS[mt] = MFMA32(frag_perm(Kb, 136, 32 * mt + r, ks, h), sp, KS[mt]); QS[mt] = MFMA32(frag_perm(Qb, 136, 32 * mt + r, ks, h), sp, QS[mt]); }
;                 }
;                 __builtin_amdgcn_iglp_opt(0);
; #pragma unroll
;                 for (int mt = 0; mt < 2; ++mt)
; #pragma unroll
;                     for (int g4 = 0; g4 < 4; ++g4) { const int i0 = 32 * mt + 8 * g4 + 4 * h;
;                         const f32x4 bv = *(const LAS f32x4*)(sc_beta + i0), ev = *(const LAS f32x4*)(sc_eg + i0);
; #pragma unroll
;                         for (int e = 0; e < 4; ++e) { const int x = 4 * g4 + e; KS[mt][x] = bv[e] * (bf2f(Vb[(i0 + e) * 128 + 32 * w + r]) - ev[e] * KS[mt][x]); } }
;                 bf16x8 Xp[4];
; #pragma unroll
;                 for (int ks = 0; ks < 4; ++ks) Xp[ks] = pack_step(KS[ks >> 1], ks & 1);
	v_mfma_f32_32x32x16_bf16 v[66:81], v[150:153], v[230:233], v[66:81]
	v_cvt_pk_bf16_f32 v238, v26, v27
	v_cvt_pk_bf16_f32 v240, v30, v31
	v_cvt_pk_bf16_f32 v239, v28, v29
	v_cvt_pk_bf16_f32 v241, v32, v33
	v_permlane32_swap_b32_e32 v238, v240
	ds_read_b128 v[150:153], v212 offset:8832
	v_permlane32_swap_b32_e32 v239, v241
	s_waitcnt lgkmcnt(8)
	v_mfma_f32_32x32x16_bf16 v[66:81], v[154:157], v[234:237], v[66:81]
	v_cvt_pk_bf16_f32 v242, v2, v3
	v_cvt_pk_bf16_f32 v244, v6, v7
	v_cvt_pk_bf16_f32 v243, v4, v5
	v_cvt_pk_bf16_f32 v245, v8, v9
	v_permlane32_swap_b32_e32 v242, v244
	ds_read_b128 v[154:157], v212 offset:8864
	v_permlane32_swap_b32_e32 v243, v245
	s_waitcnt lgkmcnt(8)
	v_mfma_f32_32x32x16_bf16 v[66:81], v[158:161], v[238:241], v[66:81]
	v_cvt_pk_bf16_f32 v246, v10, v11
	v_cvt_pk_bf16_f32 v248, v14, v15
	v_cvt_pk_bf16_f32 v247, v12, v13
	v_cvt_pk_bf16_f32 v249, v16, v17
	v_permlane32_swap_b32_e32 v246, v248
	ds_read_b128 v[158:161], v212 offset:8896
	v_permlane32_swap_b32_e32 v247, v249
	ds_read_u16 v114, v213 offset:34816
	ds_read_u16 v115, v213 offset:35072
	ds_read_u16 v116, v213 offset:35328
	ds_read_u16 v117, v213 offset:35584
	ds_read_b128 v[118:121], v214 offset:0
	ds_read_b128 v[122:125], v214 offset:512
	s_waitcnt lgkmcnt(14)
	v_mfma_f32_32x32x16_bf16 v[66:81], v[162:165], v[242:245], v[66:81]
	ds_read_u16 v126, v213 offset:36864
	ds_read_u16 v127, v213 offset:37120
	ds_read_u16 v128, v213 offset:37376
	ds_read_u16 v129, v213 offset:37632
	ds_read_b128 v[130:133], v214 offset:32
	ds_read_b128 v[134:137], v214 offset:544
	ds_read_b128 v[162:165], v212 offset:8928
	v_mfma_f32_32x32x16_bf16 v[66:81], v[166:169], v[246:249], v[66:81]
	ds_read_b128 v[166:169], v212 offset:17408
	v_mfma_f32_32x32x16_bf16 v[82:97], v[138:141], v[218:221], 0
	ds_read_b128 v[138:141], v212 offset:17440
	v_mfma_f32_32x32x16_bf16 v[82:97], v[170:173], v[222:225], v[82:97]
	ds_read_b128 v[170:173], v212 offset:17472
	v_mfma_f32_32x32x16_bf16 v[82:97], v[142:145], v[226:229], v[82:97]
	v_lshlrev_b32_e32 v114, 16, v114
	s_waitcnt lgkmcnt(14)
	v_lshlrev_b32_e32 v115, 16, v115
	s_waitcnt lgkmcnt(13)
	v_lshlrev_b32_e32 v116, 16, v116
	s_waitcnt lgkmcnt(12)
	v_lshlrev_b32_e32 v117, 16, v117
	s_waitcnt lgkmcnt(10)
	v_fma_f32 v114, -v66, v122, v114
	v_fma_f32 v115, -v67, v123, v115
	v_fma_f32 v116, -v68, v124, v116
	v_fma_f32 v117, -v69, v125, v117
	v_mul_f32_e32 v66, v118, v114
	v_mul_f32_e32 v67, v119, v115
	v_mul_f32_e32 v68, v120, v116
	v_mul_f32_e32 v69, v121, v117
	ds_read_u16 v114, v213 offset:38912
	ds_read_u16 v115, v213 offset:39168
	ds_read_u16 v116, v213 offset:39424
	ds_read_u16 v117, v213 offset:39680
	ds_read_b128 v[118:121], v214 offset:64
	ds_read_b128 v[122:125], v214 offset:576
	ds_read_b128 v[142:145], v212 offset:17504
	v_mfma_f32_32x32x16_bf16 v[82:97], v[146:149], v[230:233], v[82:97]
	v_lshlrev_b32_e32 v126, 16, v126
	v_lshlrev_b32_e32 v127, 16, v127
	s_waitcnt lgkmcnt(14)
	v_lshlrev_b32_e32 v128, 16, v128
	s_waitcnt lgkmcnt(13)
	v_lshlrev_b32_e32 v129, 16, v129
	s_waitcnt lgkmcnt(11)
	v_fma_f32 v126, -v70, v134, v126
	v_fma_f32 v127, -v71, v135, v127
	v_fma_f32 v128, -v72, v136, v128
	v_fma_f32 v129, -v73, v137, v129
	v_mul_f32_e32 v70, v130, v126
	v_mul_f32_e32 v71, v131, v127
	v_mul_f32_e32 v72, v132, v128
	v_mul_f32_e32 v73, v133, v129
	ds_read_u16 v126, v213 offset:40960
	ds_read_u16 v127, v213 offset:41216
	ds_read_u16 v128, v213 offset:41472
	ds_read_u16 v129, v213 offset:41728
	ds_read_b128 v[130:133], v214 offset:96
	ds_read_b128 v[134:137], v214 offset:608
	ds_read_b128 v[146:149], v212 offset:17536
	v_mfma_f32_32x32x16_bf16 v[82:97], v[150:153], v[234:237], v[82:97]
	v_cvt_pk_bf16_f32 v150, v66, v67
	v_cvt_pk_bf16_f32 v152, v70, v71
	v_cvt_pk_bf16_f32 v151, v68, v69
	v_cvt_pk_bf16_f32 v153, v72, v73
	v_permlane32_swap_b32_e32 v150, v152
	s_nop 0
	v_permlane32_swap_b32_e32 v151, v153
	s_waitcnt lgkmcnt(13)
	v_lshlrev_b32_e32 v114, 16, v114
	s_waitcnt lgkmcnt(12)
	v_lshlrev_b32_e32 v115, 16, v115
	s_waitcnt lgkmcnt(11)
	v_lshlrev_b32_e32 v116, 16, v116
	s_waitcnt lgkmcnt(10)
	v_lshlrev_b32_e32 v117, 16, v117
	s_waitcnt lgkmcnt(8)
	v_fma_f32 v114, -v74, v122, v114
	v_fma_f32 v115, -v75, v123, v115
	v_fma_f32 v116, -v76, v124, v116
	v_fma_f32 v117, -v77, v125, v117
	v_mul_f32_e32 v74, v118, v114
	v_mul_f32_e32 v75, v119, v115
	v_mul_f32_e32 v76, v120, v116
	v_mul_f32_e32 v77, v121, v117
	v_mfma_f32_32x32x16_bf16 v[82:97], v[154:157], v[238:241], v[82:97]
	s_waitcnt lgkmcnt(6)
	v_lshlrev_b32_e32 v126, 16, v126
	s_waitcnt lgkmcnt(5)
	v_lshlrev_b32_e32 v127, 16, v127
	s_waitcnt lgkmcnt(4)
	v_lshlrev_b32_e32 v128, 16, v128
	s_waitcnt lgkmcnt(3)
	v_lshlrev_b32_e32 v129, 16, v129
	s_waitcnt lgkmcnt(1)
	v_fma_f32 v126, -v78, v134, v126
	v_fma_f32 v127, -v79, v135, v127
	v_fma_f32 v128, -v80, v136, v128
	v_fma_f32 v129, -v81, v137, v129
	v_mul_f32_e32 v78, v130, v126
	v_mul_f32_e32 v79, v131, v127
	v_mul_f32_e32 v80, v132, v128
	v_mul_f32_e32 v81, v133, v129
	ds_read_u16 v114, v213 offset:43008
	ds_read_u16 v115, v213 offset:43264
	ds_read_u16 v116, v213 offset:43520
	ds_read_u16 v117, v213 offset:43776
	ds_read_b128 v[118:121], v214 offset:128
	ds_read_b128 v[122:125], v214 offset:640
	ds_read_b128 v[154:157], v212 offset:17568
	v_mfma_f32_32x32x16_bf16 v[82:97], v[158:161], v[242:245], v[82:97]
	v_cvt_pk_bf16_f32 v158, v74, v75
	v_cvt_pk_bf16_f32 v160, v78, v79
	v_cvt_pk_bf16_f32 v159, v76, v77
	v_cvt_pk_bf16_f32 v161, v80, v81
	v_permlane32_swap_b32_e32 v158, v160
	s_nop 0
	v_permlane32_swap_b32_e32 v159, v161
	ds_read_u16 v126, v213 offset:45056
	ds_read_u16 v127, v213 offset:45312
	ds_read_u16 v128, v213 offset:45568
	ds_read_u16 v129, v213 offset:45824
	ds_read_b128 v[130:133], v214 offset:160
	ds_read_b128 v[134:137], v214 offset:672
	v_mfma_f32_32x32x16_bf16 v[82:97], v[162:165], v[246:249], v[82:97]
	ds_read_b128 v[162:165], v212 offset:17600
	v_mfma_f32_32x32x16_bf16 v[98:113], v[166:169], v[218:221], 0
	ds_read_b128 v[166:169], v212 offset:17632
	v_mfma_f32_32x32x16_bf16 v[98:113], v[138:141], v[222:225], v[98:113]
	ds_read_b128 v[138:141], v212 offset:26112
	v_mfma_f32_32x32x16_bf16 v[98:113], v[170:173], v[226:229], v[98:113]
	v_lshlrev_b32_e32 v114, 16, v114
	s_waitcnt lgkmcnt(14)
; #define LAS __attribute__((address_space(3)))
; #define MFMA32(a, b, c) __builtin_amdgcn_mfma_f32_32x32x16_bf16((a), (b), (c), 0, 0, 0)
; template <int VAR> __device__ __forceinline__ void dn_scan3(LAS unsigned char* lds, const bf16_t* P, const float* AB, const bf16_t* TP, bf16_t* OB) {
;     ...
;                 for (int mt = 0; mt < 2; ++mt)
; #pragma unroll
;                     for (int g4 = 0; g4 < 4; ++g4) { const int i0 = 32 * mt + 8 * g4 + 4 * h;
;                         const f32x4 bv = *(const LAS f32x4*)(sc_beta + i0), ev = *(const LAS f32x4*)(sc_eg + i0);
; #pragma unroll
;                         for (int e = 0; e < 4; ++e) { const int x = 4 * g4 + e; KS[mt][x] = bv[e] * (bf2f(Vb[(i0 + e) * 128 + 32 * w + r]) - ev[e] * KS[mt][x]); } }
;                 bf16x8 Xp[4];
; #pragma unroll
;                 for (int ks = 0; ks < 4; ++ks) Xp[ks] = pack_step(KS[ks >> 1], ks & 1);
;                 f32x16 VN[2];
; #pragma unroll
;                 for (int mt = 0; mt < 2; ++mt) {
; #pragma unroll
;                     for (int x = 0; x < 16; ++x) VN[mt][x] = 0.f;
; #pragma unroll
;                     for (int ks = 0; ks < 4; ++ks) if (ks < 2 * mt + 2) VN[mt] = MFMA32(frag_perm(Tb, 72, 32 * mt + r, ks, h), Xp[ks], VN[mt]);
;                 }
;                 bf16x8 VNp[4];
; #pragma unroll
;                 for (int ks = 0; ks < 4; ++ks) VNp[ks] = pack_step(VN[ks >> 1], ks & 1);
; #pragma unroll
;                 for (int mt = 0; mt < 2; ++mt) {
; #pragma unroll
;                     for (int g4 = 0; g4 < 4; ++g4) { const f32x4 ev = *(const LAS f32x4*)(sc_eg + 32 * mt + 8 * g4 + 4 * h);
; #pragma unroll
;                         for (int e = 0; e < 4; ++e) QS[mt][4 * g4 + e] *= ev[e]; }
	v_lshlrev_b32_e32 v115, 16, v115
	s_waitcnt lgkmcnt(13)
	v_lshlrev_b32_e32 v116, 16, v116
	s_waitcnt lgkmcnt(12)
	v_lshlrev_b32_e32 v117, 16, v117
	s_waitcnt lgkmcnt(10)
	v_fma_f32 v114, -v82, v122, v114
	v_fma_f32 v115, -v83, v123, v115
	v_fma_f32 v116, -v84, v124, v116
	v_fma_f32 v117, -v85, v125, v117
	v_mul_f32_e32 v82, v118, v114
	v_mul_f32_e32 v83, v119, v115
	v_mul_f32_e32 v84, v120, v116
	v_mul_f32_e32 v85, v121, v117
	ds_read_u16 v114, v213 offset:47104
	ds_read_u16 v115, v213 offset:47360
	ds_read_u16 v116, v213 offset:47616
	ds_read_u16 v117, v213 offset:47872
	ds_read_b128 v[118:121], v214 offset:192
	ds_read_b128 v[122:125], v214 offset:704
	ds_read_b128 v[170:173], v212 offset:26144
	v_mfma_f32_32x32x16_bf16 v[98:113], v[142:145], v[230:233], v[98:113]
	v_lshlrev_b32_e32 v126, 16, v126
	s_waitcnt lgkmcnt(14)
	v_lshlrev_b32_e32 v127, 16, v127
	s_waitcnt lgkmcnt(13)
	v_lshlrev_b32_e32 v128, 16, v128
	s_waitcnt lgkmcnt(12)
	v_lshlrev_b32_e32 v129, 16, v129
	s_waitcnt lgkmcnt(10)
	v_fma_f32 v126, -v86, v134, v126
	v_fma_f32 v127, -v87, v135, v127
	v_fma_f32 v128, -v88, v136, v128
	v_fma_f32 v129, -v89, v137, v129
	v_mul_f32_e32 v86, v130, v126
	v_mul_f32_e32 v87, v131, v127
	v_mul_f32_e32 v88, v132, v128
	v_mul_f32_e32 v89, v133, v129
	ds_read_u16 v126, v213 offset:49152
	ds_read_u16 v127, v213 offset:49408
	ds_read_u16 v128, v213 offset:49664
	ds_read_u16 v129, v213 offset:49920
	ds_read_b128 v[130:133], v214 offset:224
	ds_read_b128 v[134:137], v214 offset:736
	ds_read_b128 v[142:145], v212 offset:26176
	v_mfma_f32_32x32x16_bf16 v[98:113], v[146:149], v[234:237], v[98:113]
	v_cvt_pk_bf16_f32 v146, v82, v83
	v_cvt_pk_bf16_f32 v148, v86, v87
	v_cvt_pk_bf16_f32 v147, v84, v85
	v_cvt_pk_bf16_f32 v149, v88, v89
	v_permlane32_swap_b32_e32 v146, v148
	s_nop 0
	v_permlane32_swap_b32_e32 v147, v149
	s_waitcnt lgkmcnt(13)
	v_lshlrev_b32_e32 v114, 16, v114
	s_waitcnt lgkmcnt(12)
	v_lshlrev_b32_e32 v115, 16, v115
	s_waitcnt lgkmcnt(11)
	v_lshlrev_b32_e32 v116, 16, v116
	s_waitcnt lgkmcnt(10)
	v_lshlrev_b32_e32 v117, 16, v117
	s_waitcnt lgkmcnt(8)
	v_fma_f32 v114, -v90, v122, v114
	v_fma_f32 v115, -v91, v123, v115
	v_fma_f32 v116, -v92, v124, v116
	v_fma_f32 v117, -v93, v125, v117
	v_mul_f32_e32 v90, v118, v114
	v_mul_f32_e32 v91, v119, v115
	v_mul_f32_e32 v92, v120, v116
	v_mul_f32_e32 v93, v121, v117
	v_mfma_f32_32x32x16_bf16 v[98:113], v[154:157], v[238:241], v[98:113]
	s_waitcnt lgkmcnt(6)
	v_lshlrev_b32_e32 v126, 16, v126
	s_waitcnt lgkmcnt(5)
	v_lshlrev_b32_e32 v127, 16, v127
	s_waitcnt lgkmcnt(4)
	v_lshlrev_b32_e32 v128, 16, v128
	s_waitcnt lgkmcnt(3)
	v_lshlrev_b32_e32 v129, 16, v129
	s_waitcnt lgkmcnt(1)
	v_fma_f32 v126, -v94, v134, v126
	v_fma_f32 v127, -v95, v135, v127
	v_fma_f32 v128, -v96, v136, v128
	v_fma_f32 v129, -v97, v137, v129
	v_mul_f32_e32 v94, v130, v126
	v_mul_f32_e32 v95, v131, v127
	v_mul_f32_e32 v96, v132, v128
	v_mul_f32_e32 v97, v133, v129
	ds_read_b128 v[154:157], v212 offset:26208
	v_mfma_f32_32x32x16_bf16 v[98:113], v[162:165], v[242:245], v[98:113]
	v_cvt_pk_bf16_f32 v162, v90, v91
	v_cvt_pk_bf16_f32 v164, v94, v95
	v_cvt_pk_bf16_f32 v163, v92, v93
	v_cvt_pk_bf16_f32 v165, v96, v97
	v_permlane32_swap_b32_e32 v162, v164
	s_nop 0
	v_permlane32_swap_b32_e32 v163, v165
	v_mfma_f32_32x32x16_bf16 v[98:113], v[166:169], v[246:249], v[98:113]
	ds_read_b32 v130, v217
	ds_read_b128 v[134:137], v214 offset:512
	ds_read_b128 v[166:169], v212 offset:26240
	v_mfma_f32_32x32x16_bf16 v[114:129], v[138:141], v[218:221], 0
	s_waitcnt lgkmcnt(2)
	v_mul_f32_e32 v50, v50, v130
	v_mul_f32_e32 v51, v51, v130
	v_mul_f32_e32 v52, v52, v130
	v_mul_f32_e32 v53, v53, v130
	v_mul_f32_e32 v54, v54, v130
	v_mul_f32_e32 v55, v55, v130
	v_mul_f32_e32 v56, v56, v130
	v_mul_f32_e32 v57, v57, v130
	ds_read_b128 v[138:141], v214 offset:544
	v_mfma_f32_32x32x16_bf16 v[114:129], v[170:173], v[222:225], v[114:129]
	v_mul_f32_e32 v58, v58, v130
	v_mul_f32_e32 v59, v59, v130
	v_mul_f32_e32 v60, v60, v130
	v_mul_f32_e32 v61, v61, v130
	v_mul_f32_e32 v62, v62, v130
	v_mul_f32_e32 v63, v63, v130
	v_mul_f32_e32 v64, v64, v130
	v_mul_f32_e32 v65, v65, v130
	v_mul_f32_e32 v34, v34, v130
	v_mul_f32_e32 v35, v35, v130
	s_waitcnt lgkmcnt(2)
	v_mul_f32_e32 v98, v98, v134
	v_mul_f32_e32 v99, v99, v135
	v_mul_f32_e32 v100, v100, v136
	v_mul_f32_e32 v101, v101, v137
	ds_read_b128 v[134:137], v214 offset:576
	ds_read_b128 v[170:173], v212 offset:26272
	v_mfma_f32_32x32x16_bf16 v[114:129], v[142:145], v[226:229], v[114:129]
	v_mul_f32_e32 v36, v36, v130
	v_mul_f32_e32 v37, v37, v130
	v_mul_f32_e32 v38, v38, v130
	v_mul_f32_e32 v39, v39, v130
	v_mul_f32_e32 v40, v40, v130
	v_mul_f32_e32 v41, v41, v130
	v_mul_f32_e32 v42, v42, v130
	v_mul_f32_e32 v43, v43, v130
	v_mul_f32_e32 v44, v44, v130
	v_mul_f32_e32 v45, v45, v130
	s_waitcnt lgkmcnt(2)
	v_mul_f32_e32 v102, v102, v138
	v_mul_f32_e32 v103, v103, v139
	v_mul_f32_e32 v104, v104, v140
	v_mul_f32_e32 v105, v105, v141
	ds_read_b128 v[138:141], v214 offset:608
	ds_read_b128 v[142:145], v212 offset:26304
	v_mfma_f32_32x32x16_bf16 v[114:129], v[154:157], v[230:233], v[114:129]
	v_mul_f32_e32 v46, v46, v130
	v_mul_f32_e32 v47, v47, v130
	v_mul_f32_e32 v48, v48, v130
	v_mul_f32_e32 v49, v49, v130
	v_mul_f32_e32 v18, v18, v130
	v_mul_f32_e32 v19, v19, v130
	v_mul_f32_e32 v20, v20, v130
	v_mul_f32_e32 v21, v21, v130
	v_mul_f32_e32 v22, v22, v130
	v_mul_f32_e32 v23, v23, v130
	s_waitcnt lgkmcnt(3)
; __device__ __forceinline__ int crow(int r, int hi) { return (r & 3) + 8 * (r >> 2) + 4 * hi; }
; #define LAS __attribute__((address_space(3)))
; __device__ __forceinline__ bf16_t f2bf(float f) { return (bf16_t)(cvtpk_s(f, 0.f) & 0xffffu); }
; __device__ __forceinline__ int crow(int x, int h) { return (x & 3) + 8 * (x >> 2) + 4 * h; }
; #define MFMA32(a, b, c) __builtin_amdgcn_mfma_f32_32x32x16_bf16((a), (b), (c), 0, 0, 0)
; template <int VAR> __device__ __forceinline__ void dn_scan3(LAS unsigned char* lds, const bf16_t* P, const float* AB, const bf16_t* TP, bf16_t* OB) {
;     ...
;                 for (int mt = 0; mt < 2; ++mt) {
; #pragma unroll
;                     for (int x = 0; x < 16; ++x) VN[mt][x] = 0.f;
; #pragma unroll
;                     for (int ks = 0; ks < 4; ++ks) if (ks < 2 * mt + 2) VN[mt] = MFMA32(frag_perm(Tb, 72, 32 * mt + r, ks, h), Xp[ks], VN[mt]);
;                 }
;                 bf16x8 VNp[4];
; #pragma unroll
;                 for (int ks = 0; ks < 4; ++ks) VNp[ks] = pack_step(VN[ks >> 1], ks & 1);
; #pragma unroll
;                 for (int mt = 0; mt < 2; ++mt) {
; #pragma unroll
;                     for (int g4 = 0; g4 < 4; ++g4) { const f32x4 ev = *(const LAS f32x4*)(sc_eg + 32 * mt + 8 * g4 + 4 * h);
; #pragma unroll
;                         for (int e = 0; e < 4; ++e) QS[mt][4 * g4 + e] *= ev[e]; }
; #pragma unroll
;                     for (int ks = 0; ks < 4; ++ks) if (ks < 2 * mt + 2) QS[mt] = MFMA32(frag_perm(Ab, 72, 32 * mt + r, ks, h), VNp[ks], QS[mt]);
;                 }
; #pragma unroll
;                 for (int mt = 0; mt < 2; ++mt)
; #pragma unroll
;                     for (int x = 0; x < 16; ++x) Vb[(32 * mt + crow(x, h)) * 128 + 32 * w + r] = f2bf(QS[mt][x]);
; #pragma unroll
;                 for (int mt = 0; mt < 2; ++mt)
; #pragma unroll
;                     for (int g4 = 0; g4 < 4; ++g4) { const f32x4 tv = *(const LAS f32x4*)(sc_tail + 32 * mt + 8 * g4 + 4 * h);
; #pragma unroll
;                         for (int e = 0; e < 4; ++e) VN[mt][4 * g4 + e] *= tv[e]; }
; #pragma unroll
;                 for (int ks = 0; ks < 4; ++ks) VNp[ks] = pack_step(VN[ks >> 1], ks & 1);
	v_mul_f32_e32 v106, v106, v134
	v_mul_f32_e32 v107, v107, v135
	v_mul_f32_e32 v108, v108, v136
	v_mul_f32_e32 v109, v109, v137
	ds_read_b128 v[154:157], v212 offset:26336
	v_mfma_f32_32x32x16_bf16 v[114:129], v[166:169], v[234:237], v[114:129]
	v_mul_f32_e32 v24, v24, v130
	v_mul_f32_e32 v25, v25, v130
	v_mul_f32_e32 v26, v26, v130
	v_mul_f32_e32 v27, v27, v130
	v_mul_f32_e32 v28, v28, v130
	v_mul_f32_e32 v29, v29, v130
	v_mul_f32_e32 v30, v30, v130
	v_mul_f32_e32 v31, v31, v130
	v_mul_f32_e32 v32, v32, v130
	v_mul_f32_e32 v33, v33, v130
	s_waitcnt lgkmcnt(2)
	v_mul_f32_e32 v110, v110, v138
	v_mul_f32_e32 v111, v111, v139
	v_mul_f32_e32 v112, v112, v140
	v_mul_f32_e32 v113, v113, v141
	ds_read_b128 v[134:137], v215 offset:51200
	ds_read_b128 v[138:141], v215 offset:51232
	v_mfma_f32_32x32x16_bf16 v[114:129], v[170:173], v[238:241], v[114:129]
	v_mul_f32_e32 v2, v2, v130
	v_mul_f32_e32 v3, v3, v130
	v_mul_f32_e32 v4, v4, v130
	v_mul_f32_e32 v5, v5, v130
	v_mul_f32_e32 v6, v6, v130
	v_mul_f32_e32 v7, v7, v130
	v_mul_f32_e32 v8, v8, v130
	v_mul_f32_e32 v9, v9, v130
	ds_read_b128 v[166:169], v215 offset:55808
	ds_read_b128 v[170:173], v215 offset:55840
	s_waitcnt lgkmcnt(5)
	v_mfma_f32_32x32x16_bf16 v[114:129], v[142:145], v[242:245], v[114:129]
	v_mul_f32_e32 v10, v10, v130
	v_mul_f32_e32 v11, v11, v130
	v_mul_f32_e32 v12, v12, v130
	v_mul_f32_e32 v13, v13, v130
	v_mul_f32_e32 v14, v14, v130
	v_mul_f32_e32 v15, v15, v130
	v_mul_f32_e32 v16, v16, v130
	v_mul_f32_e32 v17, v17, v130
	ds_read_b128 v[142:145], v215 offset:55872
	ds_read_b128 v[174:177], v215 offset:55904
	s_waitcnt lgkmcnt(6)
	v_mfma_f32_32x32x16_bf16 v[114:129], v[154:157], v[246:249], v[114:129]
	ds_read_b128 v[130:133], v214 offset:640
	ds_read_b128 v[154:157], v214 offset:672
	s_waitcnt lgkmcnt(7)
	v_mfma_f32_32x32x16_bf16 v[66:81], v[134:137], v[150:153], 0
	ds_read_b128 v[134:137], v214 offset:704
	ds_read_b128 v[218:221], v214 offset:736
	s_waitcnt lgkmcnt(8)
	v_mfma_f32_32x32x16_bf16 v[66:81], v[138:141], v[158:161], v[66:81]
	ds_read_b128 v[138:141], v214 offset:768
	ds_read_b128 v[222:225], v214 offset:800
	s_waitcnt lgkmcnt(9)
	v_mfma_f32_32x32x16_bf16 v[82:97], v[166:169], v[150:153], 0
	ds_read_b128 v[150:153], v214 offset:832
	ds_read_b128 v[166:169], v214 offset:864
	s_waitcnt lgkmcnt(10)
	v_mfma_f32_32x32x16_bf16 v[82:97], v[170:173], v[158:161], v[82:97]
	s_waitcnt lgkmcnt(7)
	v_mul_f32_e32 v114, v114, v130
	v_mul_f32_e32 v115, v115, v131
	v_mul_f32_e32 v116, v116, v132
	v_mul_f32_e32 v117, v117, v133
	s_waitcnt lgkmcnt(6)
	v_mul_f32_e32 v118, v118, v154
	v_mul_f32_e32 v119, v119, v155
	v_mul_f32_e32 v120, v120, v156
	v_mul_f32_e32 v121, v121, v157
	ds_read_b128 v[130:133], v215 offset:60416
	ds_read_b128 v[154:157], v215 offset:60448
	v_mfma_f32_32x32x16_bf16 v[82:97], v[142:145], v[146:149], v[82:97]
	s_waitcnt lgkmcnt(7)
	v_mul_f32_e32 v122, v122, v134
	v_mul_f32_e32 v123, v123, v135
	v_mul_f32_e32 v124, v124, v136
	v_mul_f32_e32 v125, v125, v137
	s_waitcnt lgkmcnt(6)
	v_mul_f32_e32 v126, v126, v218
	v_mul_f32_e32 v127, v127, v219
	v_mul_f32_e32 v128, v128, v220
	v_mul_f32_e32 v129, v129, v221
	v_mfma_f32_32x32x16_bf16 v[82:97], v[174:177], v[162:165], v[82:97]
	v_add_u32_e32 v134, s41, v211
	v_add_u32_e32 v135, s41, v201
	v_and_b32_e32 v136, 0xffff, v180
	v_lshrrev_b32_e32 v137, 16, v180
	v_add_u32_e32 v136, s41, v136
	v_add_u32_e32 v137, s41, v137
	ds_read_b64_tr_b16 v[158:159], v134 offset:0
	ds_read_b64_tr_b16 v[160:161], v135 offset:0
	ds_read_b64_tr_b16 v[162:163], v134 offset:64
	ds_read_b64_tr_b16 v[164:165], v135 offset:64
	v_cvt_pk_bf16_f32 v142, v66, v67
	v_cvt_pk_bf16_f32 v144, v70, v71
	v_cvt_pk_bf16_f32 v143, v68, v69
	v_cvt_pk_bf16_f32 v145, v72, v73
	v_cvt_pk_bf16_f32 v146, v74, v75
	v_cvt_pk_bf16_f32 v148, v78, v79
	v_cvt_pk_bf16_f32 v147, v76, v77
	v_cvt_pk_bf16_f32 v149, v80, v81
	v_permlane32_swap_b32_e32 v142, v144
	v_permlane32_swap_b32_e32 v143, v145
	v_permlane32_swap_b32_e32 v146, v148
	v_permlane32_swap_b32_e32 v147, v149
	s_waitcnt lgkmcnt(9)
	v_mul_f32_e32 v66, v66, v138
	v_mul_f32_e32 v67, v67, v139
	v_mul_f32_e32 v68, v68, v140
	v_mul_f32_e32 v69, v69, v141
	s_waitcnt lgkmcnt(8)
	v_mul_f32_e32 v70, v70, v222
	v_mul_f32_e32 v71, v71, v223
	v_mul_f32_e32 v72, v72, v224
	v_mul_f32_e32 v73, v73, v225
	s_waitcnt lgkmcnt(7)
	v_mul_f32_e32 v74, v74, v150
	v_mul_f32_e32 v75, v75, v151
	v_mul_f32_e32 v76, v76, v152
	v_mul_f32_e32 v77, v77, v153
	s_waitcnt lgkmcnt(6)
	v_mul_f32_e32 v78, v78, v166
	v_mul_f32_e32 v79, v79, v167
	v_mul_f32_e32 v80, v80, v168
	v_mul_f32_e32 v81, v81, v169
	v_cvt_pk_bf16_f32 v138, v66, v71
	v_cvt_pk_bf16_f32 v139, v76, v81
	v_cvt_pk_bf16_f32 v140, v67, v72
	v_cvt_pk_bf16_f32 v141, v77, v78
	v_cvt_pk_bf16_f32 v150, v68, v73
	v_cvt_pk_bf16_f32 v151, v74, v79
	v_cvt_pk_bf16_f32 v152, v69, v70
	v_cvt_pk_bf16_f32 v153, v75, v80
	ds_read_b64_tr_b16 v[166:167], v134 offset:128
	ds_read_b64_tr_b16 v[168:169], v135 offset:128
	ds_read_b64_tr_b16 v[170:171], v134 offset:192
	ds_read_b64_tr_b16 v[172:173], v135 offset:192
	ds_read_b64_tr_b16 v[174:175], v136 offset:0
	ds_read_b64_tr_b16 v[176:177], v137 offset:0
	ds_read_b64_tr_b16 v[218:219], v136 offset:64
	ds_read_b64_tr_b16 v[220:221], v137 offset:64
	s_waitcnt lgkmcnt(13)
	v_mfma_f32_32x32x16_bf16 v[98:113], v[130:133], v[142:145], v[98:113]
	ds_read_b128 v[130:133], v215 offset:65024
	ds_read_b128 v[222:225], v215 offset:65056
	s_waitcnt lgkmcnt(14)
; __device__ __forceinline__ int crow(int r, int hi) { return (r & 3) + 8 * (r >> 2) + 4 * hi; }
; #define LAS __attribute__((address_space(3)))
; __device__ __forceinline__ bf16_t f2bf(float f) { return (bf16_t)(cvtpk_s(f, 0.f) & 0xffffu); }
; __device__ __forceinline__ int crow(int x, int h) { return (x & 3) + 8 * (x >> 2) + 4 * h; }
; #define MFMA32(a, b, c) __builtin_amdgcn_mfma_f32_32x32x16_bf16((a), (b), (c), 0, 0, 0)
; template <int VAR> __device__ __forceinline__ void dn_scan3(LAS unsigned char* lds, const bf16_t* P, const float* AB, const bf16_t* TP, bf16_t* OB) {
;     ...
;                     for (int ks = 0; ks < 4; ++ks) if (ks < 2 * mt + 2) QS[mt] = MFMA32(frag_perm(Ab, 72, 32 * mt + r, ks, h), VNp[ks], QS[mt]);
;                 }
; #pragma unroll
;                 for (int mt = 0; mt < 2; ++mt)
; #pragma unroll
;                     for (int x = 0; x < 16; ++x) Vb[(32 * mt + crow(x, h)) * 128 + 32 * w + r] = f2bf(QS[mt][x]);
; #pragma unroll
;                 for (int mt = 0; mt < 2; ++mt)
; #pragma unroll
;                     for (int g4 = 0; g4 < 4; ++g4) { const f32x4 tv = *(const LAS f32x4*)(sc_tail + 32 * mt + 8 * g4 + 4 * h);
; #pragma unroll
;                         for (int e = 0; e < 4; ++e) VN[mt][4 * g4 + e] *= tv[e]; }
; #pragma unroll
;                 for (int ks = 0; ks < 4; ++ks) VNp[ks] = pack_step(VN[ks >> 1], ks & 1);
;                 const float dl = sc_dl[0];
; #pragma unroll
;                 for (int kt = 0; kt < 4; ++kt)
; #pragma unroll
;                     for (int x = 0; x < 16; ++x) S[kt][x] *= dl;
; #pragma unroll
;                 for (int ks = 0; ks < 4; ++ks) {
; #pragma unroll
;                     for (int kt = 0; kt < 4; ++kt) S[kt] = MFMA32(frag_tr(Kb, 136, 32 * kt, ks, lane), VNp[ks], S[kt]);
	v_mfma_f32_32x32x16_bf16 v[98:113], v[154:157], v[146:149], v[98:113]
	ds_read_b128 v[154:157], v214 offset:896
	ds_read_b128 v[226:229], v214 offset:928
	ds_read_b64_tr_b16 v[230:231], v136 offset:128
	ds_read_b64_tr_b16 v[232:233], v137 offset:128
	ds_read_b64_tr_b16 v[234:235], v136 offset:192
	ds_read_b64_tr_b16 v[236:237], v137 offset:192
	ds_read_b64_tr_b16 v[238:239], v134 offset:8704
	ds_read_b64_tr_b16 v[240:241], v135 offset:8704
	v_mfma_f32_32x32x16_bf16 v[50:65], v[158:161], v[138:141], v[50:65]
	ds_read_b128 v[158:161], v214 offset:960
	ds_read_b128 v[242:245], v214 offset:992
	v_mfma_f32_32x32x16_bf16 v[34:49], v[162:165], v[138:141], v[34:49]
	v_cvt_pk_bf16_f32 v162, v82, v83
	v_cvt_pk_bf16_f32 v164, v86, v87
	v_cvt_pk_bf16_f32 v163, v84, v85
	v_cvt_pk_bf16_f32 v165, v88, v89
	v_permlane32_swap_b32_e32 v162, v164
	s_nop 0
	v_permlane32_swap_b32_e32 v163, v165
	v_mfma_f32_32x32x16_bf16 v[18:33], v[166:169], v[138:141], v[18:33]
	v_cvt_pk_bf16_f32 v166, v90, v91
	v_cvt_pk_bf16_f32 v168, v94, v95
	v_cvt_pk_bf16_f32 v167, v92, v93
	v_cvt_pk_bf16_f32 v169, v96, v97
	v_permlane32_swap_b32_e32 v166, v168
	s_nop 0
	v_permlane32_swap_b32_e32 v167, v169
	v_mfma_f32_32x32x16_bf16 v[2:17], v[170:173], v[138:141], v[2:17]
	s_waitcnt lgkmcnt(9)
	v_mul_f32_e32 v82, v82, v154
	v_mul_f32_e32 v83, v83, v155
	v_mul_f32_e32 v84, v84, v156
	v_mul_f32_e32 v85, v85, v157
	s_waitcnt lgkmcnt(8)
	v_mul_f32_e32 v86, v86, v226
	v_mul_f32_e32 v87, v87, v227
	v_mul_f32_e32 v88, v88, v228
	v_mul_f32_e32 v89, v89, v229
	ds_read_b128 v[154:157], v215 offset:65088
	ds_read_b128 v[170:173], v215 offset:65120
	v_mfma_f32_32x32x16_bf16 v[50:65], v[174:177], v[150:153], v[50:65]
	v_cvt_pk_bf16_f32 v174, v98, s0
	ds_write_b16 v213, v174 offset:34816
	v_cvt_pk_bf16_f32 v175, v99, s0
	ds_write_b16 v213, v175 offset:35072
	s_waitcnt lgkmcnt(5)
	v_mul_f32_e32 v90, v90, v158
	v_mul_f32_e32 v91, v91, v159
	v_mul_f32_e32 v92, v92, v160
	v_mul_f32_e32 v93, v93, v161
	s_waitcnt lgkmcnt(4)
	v_mul_f32_e32 v94, v94, v242
	v_mul_f32_e32 v95, v95, v243
	v_mul_f32_e32 v96, v96, v244
	v_mul_f32_e32 v97, v97, v245
	ds_read_b64_tr_b16 v[158:159], v134 offset:8768
	ds_read_b64_tr_b16 v[160:161], v135 offset:8768
	v_mfma_f32_32x32x16_bf16 v[34:49], v[218:221], v[150:153], v[34:49]
	v_cvt_pk_bf16_f32 v176, v100, s0
	ds_write_b16 v213, v176 offset:35328
	v_cvt_pk_bf16_f32 v177, v101, s0
	ds_write_b16 v213, v177 offset:35584
	v_cvt_pk_bf16_f32 v218, v82, v87
	v_cvt_pk_bf16_f32 v219, v92, v97
	v_cvt_pk_bf16_f32 v220, v83, v88
	v_cvt_pk_bf16_f32 v221, v93, v94
	ds_read_b64_tr_b16 v[226:227], v134 offset:8832
	ds_read_b64_tr_b16 v[228:229], v135 offset:8832
	v_mfma_f32_32x32x16_bf16 v[18:33], v[230:233], v[150:153], v[18:33]
	v_cvt_pk_bf16_f32 v174, v102, s0
	ds_write_b16 v213, v174 offset:36864
	v_cvt_pk_bf16_f32 v175, v103, s0
	ds_write_b16 v213, v175 offset:37120
	v_cvt_pk_bf16_f32 v230, v84, v89
	v_cvt_pk_bf16_f32 v231, v90, v95
	v_cvt_pk_bf16_f32 v232, v85, v86
	v_cvt_pk_bf16_f32 v233, v91, v96
	v_mfma_f32_32x32x16_bf16 v[2:17], v[234:237], v[150:153], v[2:17]
	v_cvt_pk_bf16_f32 v176, v104, s0
	ds_write_b16 v213, v176 offset:37376
	v_cvt_pk_bf16_f32 v177, v105, s0
	ds_write_b16 v213, v177 offset:37632
	v_mfma_f32_32x32x16_bf16 v[114:129], v[130:133], v[142:145], v[114:129]
	v_cvt_pk_bf16_f32 v174, v106, s0
	ds_write_b16 v213, v174 offset:38912
	v_cvt_pk_bf16_f32 v175, v107, s0
	ds_write_b16 v213, v175 offset:39168
	ds_read_b64_tr_b16 v[130:131], v134 offset:8896
	ds_read_b64_tr_b16 v[132:133], v135 offset:8896
	ds_read_b64_tr_b16 v[138:139], v136 offset:8704
	ds_read_b64_tr_b16 v[140:141], v137 offset:8704
	v_mfma_f32_32x32x16_bf16 v[114:129], v[222:225], v[146:149], v[114:129]
	v_cvt_pk_bf16_f32 v176, v108, s0
	ds_write_b16 v213, v176 offset:39424
	v_cvt_pk_bf16_f32 v177, v109, s0
	ds_write_b16 v213, v177 offset:39680
	ds_read_b64_tr_b16 v[142:143], v136 offset:8768
	ds_read_b64_tr_b16 v[144:145], v137 offset:8768
	ds_read_b64_tr_b16 v[146:147], v136 offset:8832
	ds_read_b64_tr_b16 v[148:149], v137 offset:8832
	v_mfma_f32_32x32x16_bf16 v[114:129], v[154:157], v[162:165], v[114:129]
	v_cvt_pk_bf16_f32 v174, v110, s0
	ds_write_b16 v213, v174 offset:40960
	v_cvt_pk_bf16_f32 v175, v111, s0
	ds_write_b16 v213, v175 offset:41216
	ds_read_b64_tr_b16 v[150:151], v136 offset:8896
	ds_read_b64_tr_b16 v[152:153], v137 offset:8896
	v_mfma_f32_32x32x16_bf16 v[114:129], v[170:173], v[166:169], v[114:129]
	v_cvt_pk_bf16_f32 v176, v112, s0
	ds_write_b16 v213, v176 offset:41472
	v_cvt_pk_bf16_f32 v177, v113, s0
	ds_write_b16 v213, v177 offset:41728
	ds_read_b32 v154, v179 offset:34816
	ds_read_b32 v155, v179 offset:35840
	ds_read_b32 v156, v179 offset:36864
	ds_read_b32 v157, v179 offset:37888
	ds_read_b32 v162, v179 offset:38912
	ds_read_b32 v163, v179 offset:39936
	ds_read_b32 v164, v179 offset:40960
	ds_read_b32 v165, v179 offset:41984
	v_mfma_f32_32x32x16_bf16 v[50:65], v[238:241], v[218:221], v[50:65]
	v_cvt_pk_bf16_f32 v174, v114, s0
	ds_write_b16 v213, v174 offset:43008
	v_cvt_pk_bf16_f32 v175, v115, s0
	ds_write_b16 v213, v175 offset:43264
	v_cvt_pk_bf16_f32 v176, v116, s0
	ds_write_b16 v213, v176 offset:43520
	v_cvt_pk_bf16_f32 v177, v117, s0
	ds_write_b16 v213, v177 offset:43776
	v_add_u32_e32 v195, s60, v194
	s_waitcnt lgkmcnt(11)
; #define LAS __attribute__((address_space(3)))
; #define BAR_LDS() do { asm volatile("s_waitcnt lgkmcnt(0)" ::: "memory"); __builtin_amdgcn_s_barrier(); asm volatile("" ::: "memory"); } while (0)
; #define MFMA32(a, b, c) __builtin_amdgcn_mfma_f32_32x32x16_bf16((a), (b), (c), 0, 0, 0)
; template <int VAR> __device__ __forceinline__ void dn_scan3(LAS unsigned char* lds, const bf16_t* P, const float* AB, const bf16_t* TP, bf16_t* OB) {
;     ...
;                         for (int v = 0; v < 16; ++v) { const int ip_ = r0 + 4 * v, i_ = dir ? 63 - ip_ : ip_;
;                             atomic_add_bf16x8(OB + (size_t)(rbo * 64 + i_) * 2048 + vh * 128 + c8, *(const LAS u32x4*)(Vb + ip_ * 128 + c8)); }
;     ...
;                 for (int ks = 0; ks < 4; ++ks) {
; #pragma unroll
;                     for (int kt = 0; kt < 4; ++kt) S[kt] = MFMA32(frag_tr(Kb, 136, 32 * kt, ks, lane), VNp[ks], S[kt]);
;                 }
;                 }
;                 BAR_LDS();
;             }
	global_atomic_pk_add_bf16 v195, v154, s[42:43]
	v_add_u32_e32 v200, s61, v194
	s_waitcnt lgkmcnt(10)
	global_atomic_pk_add_bf16 v200, v155, s[42:43]
	v_mfma_f32_32x32x16_bf16 v[34:49], v[158:161], v[218:221], v[34:49]
	v_cvt_pk_bf16_f32 v174, v118, s0
	ds_write_b16 v213, v174 offset:45056
	v_cvt_pk_bf16_f32 v175, v119, s0
	ds_write_b16 v213, v175 offset:45312
	v_cvt_pk_bf16_f32 v176, v120, s0
	ds_write_b16 v213, v176 offset:45568
	v_cvt_pk_bf16_f32 v177, v121, s0
	ds_write_b16 v213, v177 offset:45824
	v_add_u32_e32 v195, s62, v195
	s_waitcnt lgkmcnt(13)
	global_atomic_pk_add_bf16 v195, v156, s[42:43]
	v_add_u32_e32 v200, s62, v200
	s_waitcnt lgkmcnt(12)
	global_atomic_pk_add_bf16 v200, v157, s[42:43]
	v_mfma_f32_32x32x16_bf16 v[18:33], v[226:229], v[218:221], v[18:33]
	v_cvt_pk_bf16_f32 v174, v122, s0
	ds_write_b16 v213, v174 offset:47104
	v_cvt_pk_bf16_f32 v175, v123, s0
	ds_write_b16 v213, v175 offset:47360
	v_cvt_pk_bf16_f32 v176, v124, s0
	ds_write_b16 v213, v176 offset:47616
	v_cvt_pk_bf16_f32 v177, v125, s0
	ds_write_b16 v213, v177 offset:47872
	v_add_u32_e32 v195, s62, v195
	global_atomic_pk_add_bf16 v195, v162, s[42:43]
	v_add_u32_e32 v200, s62, v200
	s_waitcnt lgkmcnt(14)
	global_atomic_pk_add_bf16 v200, v163, s[42:43]
	v_mfma_f32_32x32x16_bf16 v[2:17], v[130:133], v[218:221], v[2:17]
	v_cvt_pk_bf16_f32 v174, v126, s0
	ds_write_b16 v213, v174 offset:49152
	v_cvt_pk_bf16_f32 v175, v127, s0
	ds_write_b16 v213, v175 offset:49408
	v_cvt_pk_bf16_f32 v176, v128, s0
	ds_write_b16 v213, v176 offset:49664
	v_cvt_pk_bf16_f32 v177, v129, s0
	ds_write_b16 v213, v177 offset:49920
	v_add_u32_e32 v195, s62, v195
	global_atomic_pk_add_bf16 v195, v164, s[42:43]
	v_add_u32_e32 v200, s62, v200
	global_atomic_pk_add_bf16 v200, v165, s[42:43]
	v_mfma_f32_32x32x16_bf16 v[50:65], v[138:141], v[230:233], v[50:65]
	ds_read_b32 v130, v179 offset:43008
	ds_read_b32 v131, v179 offset:44032
	ds_read_b32 v132, v179 offset:45056
	ds_read_b32 v133, v179 offset:46080
	ds_read_b32 v138, v179 offset:47104
	ds_read_b32 v139, v179 offset:48128
	ds_read_b32 v140, v179 offset:49152
	ds_read_b32 v141, v179 offset:50176
	v_mfma_f32_32x32x16_bf16 v[34:49], v[142:145], v[230:233], v[34:49]
	v_add_u32_e32 v195, s62, v195
	s_waitcnt lgkmcnt(7)
	global_atomic_pk_add_bf16 v195, v130, s[42:43]
	v_add_u32_e32 v200, s62, v200
	s_waitcnt lgkmcnt(6)
	global_atomic_pk_add_bf16 v200, v131, s[42:43]
	v_mfma_f32_32x32x16_bf16 v[18:33], v[146:149], v[230:233], v[18:33]
	v_add_u32_e32 v195, s62, v195
	s_waitcnt lgkmcnt(5)
	global_atomic_pk_add_bf16 v195, v132, s[42:43]
	v_add_u32_e32 v200, s62, v200
	s_waitcnt lgkmcnt(4)
	global_atomic_pk_add_bf16 v200, v133, s[42:43]
	v_mfma_f32_32x32x16_bf16 v[2:17], v[150:153], v[230:233], v[2:17]
	v_add_u32_e32 v195, s62, v195
	s_waitcnt lgkmcnt(3)
	global_atomic_pk_add_bf16 v195, v138, s[42:43]
	v_add_u32_e32 v200, s62, v200
	s_waitcnt lgkmcnt(2)
	global_atomic_pk_add_bf16 v200, v139, s[42:43]
	v_add_u32_e32 v195, s62, v195
	s_waitcnt lgkmcnt(1)
	global_atomic_pk_add_bf16 v195, v140, s[42:43]
	v_add_u32_e32 v200, s62, v200
	s_waitcnt lgkmcnt(0)
	global_atomic_pk_add_bf16 v200, v141, s[42:43]
	s_waitcnt lgkmcnt(0)
	s_barrier
	s_add_i32 s40, s40, 1
	s_cmpk_lg_i32 s40, 0x104
	s_cbranch_scc1 .LBB0_377
	s_setprio 0
